# GDN pre: gates on the conv-idle wave, conv waves load before the gates barrier, wave roles permuted so heavy conv roles do not share a SIMD; gate-phase row loop pipelined
# speedup vs baseline: 1.0535x; 1.0031x over previous
; DI void gdn_unit_decode(int u, int& kind, int& b, int& c, int& h) { if (u < 2064) { kind = 0; b = u / 516; const int r = u % 516; c = r >> 2; h = r & 3; } else { kind = 1; b = (u - 2064) >> 2; c = 0; h = u & 3; } }
; DI void gdn_pre_unit(const Prm& p, unsigned char* lds0, int u, int tid, int wid, int lane) {
;     int loff = 0; asm volatile("" : "+s"(loff)); unsigned char* lds = lds0 + loff;
;     bf16_t* qL = (bf16_t*)(lds + GP_Q); bf16_t* kL = (bf16_t*)(lds + GP_K); bf16_t* kegL = (bf16_t*)(lds + GP_KEG); bf16_t* vtL = (bf16_t*)(lds + GP_VT); bf16_t* kdL = (bf16_t*)(lds + GP_KD);
;     bf16_t* tbL = (bf16_t*)(lds + GP_TB); float* AL = (float*)(lds + GP_A); float* gL = (float*)(lds + GP_G);
;     unsigned char* ex = p.ws + W_EX + (size_t)u * EXB;
;     int kind, b, c, h; gdn_unit_decode(u, kind, b, c, h);
;     const int lr = lane & 31, hi = lane >> 5;
;     __syncthreads();
;     if (wid == 0) { float gc, beta; gdn_gates(p, kind, b, c, h, lane, gc, beta); gL[lane] = gc; gL[64 + lane] = beta; const float eg = __expf(gc); gL[128 + lane] = eg; ((float*)(ex + 24576))[lane] = eg; }
;     __syncthreads();
;     const float gl = gL[63];
;     if (wid < 6) { const int part = wid % 3, th = wid / 3;
; DI void phase_gdn_pre(const Prm& p, unsigned char* lds, int tid, int wid, int lane) {
;     for (int u = blockIdx.x; u < NTB; u += gridDim.x) { int lv = lane, tv = tid; asm volatile("" : "+v"(lv), "+v"(tv)); gdn_pre_unit(p, lds, u, tv, wid, lv); }
.LBB0_1140:
	v_mov_b32_e32 v36, v212
	v_lshrrev_b32_e32 v100, 6, v212
	v_lshlrev_b32_e32 v100, 2, v100
	v_mov_b32_e32 v101, 0x74653210
	v_lshrrev_b32_e32 v100, v100, v101
	v_and_b32_e32 v100, 7, v100
	v_and_b32_e32 v101, 63, v212
	v_lshl_or_b32 v36, v100, 6, v101
	s_waitcnt vmcnt(0)
	s_barrier
	s_cmpk_gt_i32 s3, 0x88f
	v_readfirstlane_b32 s0, v36
	s_cbranch_scc1 .LBB0_1659
	s_ashr_i32 s2, s0, 6
	s_cmp_eq_u32 s2, 6
	s_cselect_b64 s[24:25], -1, 0
	s_cmp_lt_i32 s2, 6
	s_mul_hi_i32 s0, s2, 0x55555556
	s_cselect_b64 s[26:27], -1, 0
	s_lshr_b32 s1, s0, 31
	s_add_i32 s4, s0, s1
	s_mul_i32 s0, s4, 3
	v_writelane_b32 v246, s56, 16
	s_sub_i32 s5, s2, s0
	s_lshl_b32 s0, s5, 9
	v_writelane_b32 v246, s57, 17
	s_lshl_b32 s71, s4, 5
	v_writelane_b32 v246, s0, 18
	s_add_i32 s0, s71, -3
	s_cmp_lt_i32 s2, 3
	v_writelane_b32 v246, s0, 19
	s_cselect_b64 s[0:1], -1, 0
	v_writelane_b32 v246, s0, 20
	s_cmp_gt_i32 s2, 2
	s_cselect_b64 s[62:63], -1, 0
	v_writelane_b32 v246, s1, 21
	s_add_i32 s0, s71, -2
	v_writelane_b32 v246, s0, 22
	s_or_b32 s0, s71, 1
	v_writelane_b32 v246, s0, 23
	s_ashr_i32 s0, s0, 31
	v_writelane_b32 v246, s0, 24
	s_add_i32 s0, s71, -1
	v_writelane_b32 v246, s0, 25
	s_or_b32 s0, s71, 2
	s_ashr_i32 s87, s71, 31
	v_writelane_b32 v246, s0, 26
	s_ashr_i32 s0, s0, 31
	s_cmp_lg_u32 s5, 2
	s_cselect_b64 s[72:73], -1, 0
	s_cmp_lg_u32 s5, 0
	v_writelane_b32 v246, s0, 27
	s_mov_b32 s1, 0
	s_cselect_b64 s[54:55], -1, 0
	s_cmp_eq_u32 s5, 0
	v_writelane_b32 v246, s0, 28
	s_cselect_b64 s[64:65], -1, 0
	s_mov_b64 s[80:81], s[22:23]
	v_writelane_b32 v246, s1, 29
	s_and_b64 s[0:1], s[64:65], exec
	s_cselect_b32 s86, 0, 32
	s_cmp_eq_u32 s5, 2
	s_cselect_b32 s0, 32, 0
	v_writelane_b32 v246, s0, 30
	s_or_b32 s0, s86, 1
	v_writelane_b32 v246, s0, 31
	s_or_b32 s0, s86, 2
	v_writelane_b32 v246, s0, 32
	s_or_b32 s0, s86, 3
	v_writelane_b32 v246, s0, 33
	s_or_b32 s0, s86, 8
	v_writelane_b32 v246, s0, 34
	s_or_b32 s0, s86, 9
	v_writelane_b32 v246, s0, 35
	s_or_b32 s0, s86, 10
	v_writelane_b32 v246, s0, 36
	s_or_b32 s0, s86, 11
	v_writelane_b32 v246, s0, 37
	s_or_b32 s0, s86, 16
	v_writelane_b32 v246, s0, 38
	s_or_b32 s0, s86, 17
	v_writelane_b32 v246, s0, 39
	s_or_b32 s0, s86, 18
	v_writelane_b32 v246, s0, 40
	s_or_b32 s0, s86, 19
	v_writelane_b32 v246, s0, 41
	s_or_b32 s0, s86, 24
	v_writelane_b32 v246, s0, 42
	s_or_b32 s0, s86, 25
	v_writelane_b32 v246, s0, 43
	s_or_b32 s0, s86, 26
	v_writelane_b32 v246, s0, 44
	s_or_b32 s0, s86, 27
	s_cmp_lt_i32 s2, 4
	s_cselect_b64 s[82:83], -1, 0
	s_cmp_gt_i32 s2, 3
	v_writelane_b32 v246, s0, 45
	s_cselect_b64 s[76:77], -1, 0
	s_lshl_b32 s0, s2, 4
	v_writelane_b32 v246, s0, 46
	s_lshl_b32 s0, s2, 5
	s_and_b32 s59, s0, 0x60
	s_lshl_b32 s0, s2, 7
	s_add_u32 s75, s34, 0x1a61a800
	s_addc_u32 s33, s35, 0
	v_writelane_b32 v246, s0, 47
	s_add_u32 s0, s34, 0x1da07800
	v_writelane_b32 v246, s0, 48
	s_addc_u32 s0, s35, 0
	v_writelane_b32 v246, s0, 49
	s_add_u32 s0, s34, 0x1da03800
	v_writelane_b32 v246, s0, 50
	s_addc_u32 s0, s35, 0
	v_writelane_b32 v246, s0, 51
	s_add_u32 s0, s34, 0x1da0b800
	v_writelane_b32 v246, s0, 52
	s_addc_u32 s0, s35, 0
	v_writelane_b32 v246, s0, 53
	s_lshl_b32 s0, s4, 6
	s_add_i32 s0, s0, 0
	v_writelane_b32 v246, s0, 54
	s_mul_i32 s0, s4, 0x2200
	s_add_i32 s0, s0, 0
	v_writelane_b32 v246, s0, 55
	s_lshl_b32 s0, s4, 7
	s_add_i32 s0, s0, 0
	v_writelane_b32 v246, s0, 56
	s_mul_i32 s0, s4, 0x18000
	s_mul_hi_i32 s1, s71, 0xc00
	s_add_u32 s0, s34, s0
	v_readlane_b32 s8, v247, 11
	s_addc_u32 s1, s35, s1
	v_readlane_b32 s9, v247, 12
	v_readlane_b32 s10, v247, 13
	v_readlane_b32 s11, v247, 14
	v_readlane_b32 s12, v247, 15
	v_readlane_b32 s13, v247, 16
	v_readlane_b32 s14, v247, 17
	v_readlane_b32 s15, v247, 18
	s_add_u32 s0, s0, 0x1042fc00
	v_readlane_b32 s16, v247, 19
	v_readlane_b32 s17, v247, 20
	v_readlane_b32 s18, v247, 21
	v_readlane_b32 s19, v247, 22
	s_mov_b64 s[8:9], s[12:13]
	v_writelane_b32 v246, s0, 57
	s_addc_u32 s0, s1, 0
	s_mul_i32 s4, s4, 0x30000
	s_mov_b64 s[10:11], s[14:15]
	s_mov_b64 s[12:13], s[16:17]
	s_mov_b64 s[14:15], s[18:19]
	v_writelane_b32 v246, s0, 58
	s_mul_hi_i32 s0, s71, 0x1800
	s_add_u32 s1, s14, s4
	s_addc_u32 s0, s15, s0
	s_add_u32 s1, s1, 0xa800
	v_writelane_b32 v246, s1, 59
	s_addc_u32 s0, s0, 0
	v_readlane_b32 s20, v247, 23
	v_readlane_b32 s21, v247, 24
	v_writelane_b32 v246, s0, 60
	v_and_b32_e32 v37, 63, v36
	s_mov_b32 s78, 0x800000
	v_mov_b32_e32 v33, 0
	v_cndmask_b32_e64 v38, 0, 1, s[26:27]
	s_movk_i32 s20, 0x110
	s_movk_i32 s21, 0x90
	v_mov_b32_e32 v39, 0x41b17218
	v_mov_b32_e32 v40, 0x1600
	v_mov_b32_e32 v41, 0x1800
	v_mov_b32_e32 v42, 0xc00
	s_mov_b32 s2, s3
	v_readlane_b32 s22, v247, 25
	v_readlane_b32 s23, v247, 26
	s_branch .LBB0_1144

; template <class F> DI void gdn_conv(const Prm& p, int kind, int b, int c, int col, int t0, int n, F f) {
;     f32x2 w[4];
; #pragma unroll
;     for (int j = 0; j < 4; ++j) w[j] = (f32x2){p.conv_w[j * 1536 + col], p.conv_w[j * 1536 + col + 1]};
;     f32x2 x0 = gdn_raw(p, kind, b, c, t0 - 3, col), x1 = gdn_raw(p, kind, b, c, t0 - 2, col), x2 = gdn_raw(p, kind, b, c, t0 - 1, col);
; DI void gdn_pre_unit(const Prm& p, unsigned char* lds0, int u, int tid, int wid, int lane) {
;     ...
;     __syncthreads();
;     if (wid == 0) { float gc, beta; gdn_gates(p, kind, b, c, h, lane, gc, beta); gL[lane] = gc; gL[64 + lane] = beta; const float eg = __expf(gc); gL[128 + lane] = eg; ((float*)(ex + 24576))[lane] = eg; }
;     __syncthreads();
;     const float gl = gL[63];
;     if (wid < 6) { const int part = wid % 3, th = wid / 3;
;         gdn_conv(p, kind, b, c, part * 512 + h * 128 + 2 * lane, 32 * th, 32, [&](int t, float y0, float y1) {
.LBB0_1158:
	v_cmp_ne_u32_e64 s[4:5], 1, v38
	s_andn2_b64 vcc, exec, s[26:27]
	s_waitcnt lgkmcnt(0)
	s_nop 0
	s_cbranch_vccnz .Lpre_skipbar
	s_mov_b32 s98, 0
	s_mov_b32 s99, 0
	s_mov_b32 s100, 0
	s_add_i32 s0, s58, 0x1c4fc
	v_mov_b32_e32 v0, s0
	s_lshl_b32 s0, s94, 7
	v_readlane_b32 s1, v246, 18
	s_add_i32 s0, s0, s1
	v_lshl_add_u32 v12, v34, 1, s0
	v_readlane_b32 s8, v247, 44
	v_ashrrev_i32_e32 v13, 31, v12
	v_readlane_b32 s18, v247, 54
	v_readlane_b32 s19, v247, 55
	s_nop 0
	v_readlane_b32 s9, v247, 45
	v_lshl_add_u64 v[6:7], v[12:13], 2, s[18:19]
	v_add_co_u32_e32 v2, vcc, 0x1000, v6
	global_load_dwordx2 v[0:1], v[6:7], off
	s_nop 0
	v_addc_co_u32_e32 v3, vcc, 0, v7, vcc
	v_add_co_u32_e32 v4, vcc, 0x3000, v6
	global_load_dwordx2 v[2:3], v[2:3], off offset:2048
	s_nop 0
	v_addc_co_u32_e32 v5, vcc, 0, v7, vcc
	global_load_dwordx2 v[4:5], v[4:5], off
	v_add_co_u32_e32 v6, vcc, 0x4000, v6
	v_readlane_b32 s10, v247, 46
	s_nop 0
	v_addc_co_u32_e32 v7, vcc, 0, v7, vcc
	global_load_dwordx2 v[6:7], v[6:7], off offset:2048
	s_mov_b64 s[8:9], -1
	s_mov_b64 s[0:1], 0
	s_and_b64 vcc, exec, s[68:69]
	s_mul_hi_i32 s52, s79, 3
	s_mul_i32 s89, s79, 3
	s_mov_b64 s[6:7], 0
	v_readlane_b32 s11, v247, 47
	v_readlane_b32 s12, v247, 48
	v_readlane_b32 s13, v247, 49
	v_readlane_b32 s14, v247, 50
	v_readlane_b32 s15, v247, 51
	v_readlane_b32 s16, v247, 52
	v_readlane_b32 s17, v247, 53
	v_readlane_b32 s20, v247, 56
	v_readlane_b32 s21, v247, 57
	v_readlane_b32 s22, v247, 58
	v_readlane_b32 s23, v247, 59
	s_cbranch_vccz .LBB0_1165
	s_and_b64 vcc, exec, s[62:63]
	s_cbranch_vccz .LBB0_1162
	s_lshl_b32 s6, s79, 6
	s_add_i32 s10, s6, 0x8000
	s_mov_b64 s[6:7], -1
	s_cbranch_execz .LBB0_1163
	s_branch .LBB0_1164

; DI void gdn_pre_unit(const Prm& p, unsigned char* lds0, int u, int tid, int wid, int lane) {
;     ...
;     __syncthreads();
;     const float gl = gL[63];
.Lcv_skip2:
	s_barrier
	s_add_i32 s32, s58, 0x1c4fc
	v_mov_b32_e32 v68, s32
	ds_read_b32 v27, v68
	s_waitcnt lgkmcnt(0)
	s_branch .LBB0_1212
.Lpre_skipbar:
	s_barrier
	s_branch .LBB0_1365

; DI unsigned pk2(float lo, float hi) { f32x2 v = {lo, hi}; bf16x2_t b = __builtin_convertvector(v, bf16x2_t); return __builtin_bit_cast(unsigned, b); }
; DI float bflo(unsigned u) { return __uint_as_float(u << 16); }
; DI float bfhi(unsigned u) { return __uint_as_float(u & 0xffff0000u); }
; DI float siluf(float x) { return x * __builtin_amdgcn_rcpf(1.f + __expf(-x)); }
; DI void phase_gdn_gate(const Prm& p, int gw, int ngw, int lane) {
;     bf16_t* O = (bf16_t*)(p.ws + W_XN); const bf16_t* HP = (const bf16_t*)(p.ws + W_HP);
;     for (int r = gw; r < ROW_PAD; r += ngw) {
;         u32x4* q = (u32x4*)(O + (size_t)r * D) + lane; const u32x4 u = *q; const u32x4 z = *((const u32x4*)(HP + (size_t)r * NPJ + C_Z) + lane);
;         float v[8] = {bflo(u.x), bfhi(u.x), bflo(u.y), bfhi(u.y), bflo(u.z), bfhi(u.z), bflo(u.w), bfhi(u.w)};
;         float zz[8] = {bflo(z.x), bfhi(z.x), bflo(z.y), bfhi(z.y), bflo(z.z), bfhi(z.z), bflo(z.w), bfhi(z.w)};
;         float ss = 0.f;
; #pragma unroll
;         for (int j = 0; j < 8; ++j) ss += v[j] * v[j];
;         ss = row16_sum(ss);
;         const float rstd = rsqrtf(ss * (1.f / 128.f) + 1e-6f); const int c0 = (8 * lane) & 127;
; #pragma unroll
;         for (int j = 0; j < 8; ++j) v[j] = v[j] * rstd * p.gdn_norm[c0 + j] * siluf(zz[j]);
;         u32x4 w; w.x = pk2(v[0], v[1]); w.y = pk2(v[2], v[3]); w.z = pk2(v[4], v[5]); w.w = pk2(v[6], v[7]); *q = w;
;     }
.LBB0_2040:
	s_or_b64 exec, exec, s[0:1]
	s_waitcnt vmcnt(12)
	v_mov_b32_e32 v6, v212
	s_waitcnt lgkmcnt(0)
	s_barrier
	v_readlane_b32 s1, v247, 43
	v_readfirstlane_b32 s0, v6
	s_ashr_i32 s0, s0, 6
	s_add_i32 s0, s0, s1
	s_cmp_gt_i32 s0, 0x883f
	v_and_b32_e32 v7, 63, v6
	s_cbranch_scc1 .LBB0_2043
	v_lshlrev_b32_e32 v0, 5, v7
	v_readlane_b32 s4, v247, 27
	v_and_b32_e32 v4, 0x1e0, v0
	v_mov_b32_e32 v5, 0
	v_readlane_b32 s5, v247, 28
	s_ashr_i32 s1, s0, 31
	s_mul_hi_i32 s2, s0, 0x1600
	v_lshl_add_u64 v[0:1], s[4:5], 0, v[4:5]
	s_mul_i32 s4, s0, 0x1600
	s_add_u32 s4, s34, s4
	v_lshlrev_b32_e32 v4, 4, v7
	s_addc_u32 s5, s35, s2
	v_lshl_add_u64 v[2:3], s[4:5], 0, v[4:5]
	s_mov_b64 s[4:5], 0x47cb400
	v_lshl_add_u64 v[2:3], v[2:3], 0, s[4:5]
	s_ashr_i32 s71, s70, 31
	s_lshl_b64 s[4:5], s[0:1], 11
	s_add_u32 s4, s34, s4
	s_addc_u32 s5, s35, s5
	v_lshl_add_u64 v[4:5], s[4:5], 0, v[4:5]
	s_mov_b64 s[4:5], 0x34a800
	v_lshl_add_u64 v[4:5], v[4:5], 0, s[4:5]
	s_lshl_b64 s[4:5], s[70:71], 11
	s_waitcnt vmcnt(11)
	v_mov_b32_e32 v8, 0x358637bd
	s_mov_b32 s1, 0x800000
	s_mov_b32 s2, s0
	v_readlane_b32 s6, v247, 29
	v_readlane_b32 s7, v247, 30
	v_readlane_b32 s8, v247, 31
	v_readlane_b32 s9, v247, 32
	v_readlane_b32 s10, v247, 33
	v_readlane_b32 s11, v247, 34
	v_readlane_b32 s12, v247, 35
	v_readlane_b32 s13, v247, 36
	v_readlane_b32 s14, v247, 37
	v_readlane_b32 s15, v247, 38
	v_readlane_b32 s16, v247, 39
	v_readlane_b32 s17, v247, 40
	v_readlane_b32 s18, v247, 41
	v_readlane_b32 s19, v247, 42
	global_load_dwordx4 v[18:21], v[0:1], off offset:16
	global_load_dwordx4 v[22:25], v[0:1], off
	global_load_dwordx4 v[50:53], v[4:5], off
	global_load_dwordx4 v[54:57], v[2:3], off
	v_lshl_add_u64 v[2:3], v[2:3], 0, s[56:57]
	s_waitcnt vmcnt(0)
.LBB0_2042:
	s_add_i32 s2, s2, s70
	s_cmp_lt_i32 s2, 0x8840
	s_waitcnt vmcnt(1)
	v_mov_b64_e32 v[10:11], v[50:51]
	v_mov_b64_e32 v[12:13], v[52:53]
	v_mov_b64_e32 v[14:15], v[54:55]
	v_mov_b64_e32 v[16:17], v[56:57]
	s_cbranch_scc0 .Lgt_nopf
	v_lshl_add_u64 v[58:59], v[4:5], 0, s[4:5]
	global_load_dwordx4 v[50:53], v[58:59], off
	global_load_dwordx4 v[54:57], v[2:3], off
	v_lshl_add_u64 v[2:3], v[2:3], 0, s[56:57]
.Lgt_nopf:
	v_lshlrev_b32_e32 v30, 16, v12
	v_and_b32_e32 v31, 0xffff0000, v12
	v_lshlrev_b32_e32 v12, 16, v16
	v_and_b32_e32 v33, 0xffff0000, v15
	v_lshlrev_b32_e32 v34, 16, v10
	v_and_b32_e32 v35, 0xffff0000, v10
	v_lshlrev_b32_e32 v26, 16, v13
	v_and_b32_e32 v27, 0xffff0000, v13
	v_lshlrev_b32_e32 v28, 16, v17
	v_and_b32_e32 v29, 0xffff0000, v17
	v_and_b32_e32 v13, 0xffff0000, v16
	v_lshlrev_b32_e32 v16, 16, v11
	v_and_b32_e32 v17, 0xffff0000, v11
	v_mul_f32_e32 v9, 0xbfb8aa3b, v12
	v_mul_f32_e32 v44, 0xbfb8aa3b, v33
	v_pk_mul_f32 v[40:41], v[34:35], v[34:35]
	v_pk_mul_f32 v[38:39], v[16:17], v[16:17]
	v_exp_f32_e32 v9, v9
	v_exp_f32_e32 v44, v44
	v_add_f32_e32 v40, v40, v41
	v_add_f32_e32 v38, v38, v40
	v_pk_mul_f32 v[36:37], v[30:31], v[30:31]
	v_add_f32_e32 v38, v39, v38
	v_add_f32_e32 v36, v36, v38
	v_lshlrev_b32_e32 v32, 16, v15
	v_lshlrev_b32_e32 v10, 16, v14
	v_and_b32_e32 v11, 0xffff0000, v14
	v_pk_mul_f32 v[14:15], v[26:27], v[26:27]
	v_add_f32_e32 v9, 1.0, v9
	v_add_f32_e32 v40, 1.0, v44
	v_add_f32_e32 v44, v37, v36
	v_rcp_f32_e32 v36, v9
	v_add_f32_e32 v9, v14, v44
	v_add_f32_e32 v9, v15, v9
	v_mul_f32_e32 v42, 0xbfb8aa3b, v13
	v_mul_f32_e32 v43, 0xbfb8aa3b, v32
	v_add_f32_dpp v9, v9, v9 quad_perm:[1,0,3,2] row_mask:0xf bank_mask:0xf bound_ctrl:1
	v_exp_f32_e32 v42, v42
	v_exp_f32_e32 v43, v43
	v_add_f32_dpp v9, v9, v9 quad_perm:[2,3,0,1] row_mask:0xf bank_mask:0xf bound_ctrl:1
	v_mul_f32_e32 v45, 0xbfb8aa3b, v10
	v_mul_f32_e32 v46, 0xbfb8aa3b, v11
	v_add_f32_dpp v9, v9, v9 row_half_mirror row_mask:0xf bank_mask:0xf bound_ctrl:1
	v_mul_f32_e32 v47, 0xbfb8aa3b, v28
	v_mul_f32_e32 v48, 0xbfb8aa3b, v29
	v_add_f32_dpp v9, v9, v9 row_mirror row_mask:0xf bank_mask:0xf bound_ctrl:1
	v_fmamk_f32 v9, v9, 0x3c000000, v8
	v_exp_f32_e32 v45, v45
	v_exp_f32_e32 v46, v46
	v_exp_f32_e32 v41, v47
	v_exp_f32_e32 v47, v48
	v_mul_f32_e32 v14, 0x4b800000, v9
	v_cmp_gt_f32_e32 vcc, s1, v9
	v_add_f32_e32 v38, 1.0, v42
	v_add_f32_e32 v39, 1.0, v43
	v_cndmask_b32_e32 v9, v9, v14, vcc
	v_rcp_f32_e32 v37, v38
	v_rcp_f32_e32 v38, v39
	v_rcp_f32_e32 v39, v40
	v_rsq_f32_e32 v9, v9
	v_add_f32_e32 v42, 1.0, v45
	v_add_f32_e32 v43, 1.0, v46
	v_add_f32_e32 v45, 1.0, v41
	v_add_f32_e32 v46, 1.0, v47
	v_rcp_f32_e32 v40, v42
	v_rcp_f32_e32 v41, v43
	v_rcp_f32_e32 v42, v45
	v_rcp_f32_e32 v43, v46
	v_pk_mul_f32 v[14:15], v[38:39], v[32:33]
	v_mul_f32_e32 v32, 0x45800000, v9
	v_cndmask_b32_e32 v32, v9, v32, vcc
	v_pk_mul_f32 v[34:35], v[32:33], v[34:35] op_sel_hi:[0,1]
	v_pk_mul_f32 v[16:17], v[32:33], v[16:17] op_sel_hi:[0,1]
	v_pk_mul_f32 v[30:31], v[32:33], v[30:31] op_sel_hi:[0,1]
	v_pk_mul_f32 v[26:27], v[32:33], v[26:27] op_sel_hi:[0,1]
	v_pk_mul_f32 v[12:13], v[36:37], v[12:13]
	v_pk_mul_f32 v[10:11], v[40:41], v[10:11]
	v_pk_mul_f32 v[28:29], v[42:43], v[28:29]
	v_pk_mul_f32 v[34:35], v[22:23], v[34:35]
	v_pk_mul_f32 v[16:17], v[24:25], v[16:17]
	v_pk_mul_f32 v[30:31], v[18:19], v[30:31]
	v_pk_mul_f32 v[26:27], v[20:21], v[26:27]
	v_pk_mul_f32 v[10:11], v[10:11], v[34:35]
	v_pk_mul_f32 v[14:15], v[14:15], v[16:17]
	v_pk_mul_f32 v[12:13], v[12:13], v[30:31]
	v_pk_mul_f32 v[16:17], v[28:29], v[26:27]
	v_cvt_pk_bf16_f32 v10, v10, v11
	v_cvt_pk_bf16_f32 v11, v14, v15
	v_cvt_pk_bf16_f32 v12, v12, v13
	v_cvt_pk_bf16_f32 v13, v16, v17
	global_store_dwordx4 v[4:5], v[10:13], off
	v_lshl_add_u64 v[4:5], v[4:5], 0, s[4:5]
	s_cbranch_scc1 .LBB0_2042
